# v92 + phase 0 row loop: one dword-per-lane load prefetches the prompt row two iterations ahead into L2
# speedup vs baseline: 1.0105x; 1.0010x over previous
.LBB0_808:
	s_or_b64 exec, exec, s[36:37]
	v_lshlrev_b32_e32 v64, 2, v16
	v_lshl_add_u64 v[0:1], v[0:1], 0, v[64:65]
	v_readlane_b32 s22, v212, 36
	v_lshlrev_b32_e32 v100, 4, v16
	v_mov_b32_e32 v101, 0
	s_lshl_b32 s22, s22, 1
	v_lshl_add_u64 v[100:101], v[22:23], 0, v[100:101]
	v_add_u32_e32 v102, s22, v20
	s_lshl_b32 s22, s22, 12
	s_mov_b32 s23, 0
	v_cmp_ge_i32_e32 vcc, s43, v102
	v_lshl_add_u64 v[100:101], v[100:101], 0, s[22:23]
	v_cndmask_b32_e32 v100, v0, v100, vcc
	v_cndmask_b32_e32 v101, v1, v101, vcc
	global_load_dwordx4 v[12:15], v[0:1], off
	global_load_dwordx4 v[8:11], v[0:1], off offset:1024
	global_load_dwordx4 v[4:7], v[0:1], off offset:2048
	s_nop 0
	global_load_dwordx4 v[0:3], v[0:1], off offset:3072
	global_load_dword v102, v[100:101], off
	v_mov_b32_e32 v25, v65
	s_waitcnt vmcnt(4)
	v_mul_f32_e32 v28, v13, v13
	s_waitcnt vmcnt(3)
	v_mul_f32_e32 v29, v9, v9
	s_waitcnt vmcnt(2)
	v_mul_f32_e32 v30, v5, v5
	v_fmac_f32_e32 v28, v12, v12
	v_fmac_f32_e32 v29, v8, v8
	s_waitcnt vmcnt(1)
	v_mul_f32_e32 v31, v1, v1
	v_fmac_f32_e32 v30, v4, v4
	v_fmac_f32_e32 v28, v14, v14
	v_fmac_f32_e32 v29, v10, v10
	v_fmac_f32_e32 v31, v0, v0
	v_fmac_f32_e32 v30, v6, v6
	v_fmac_f32_e32 v28, v15, v15
	v_fmac_f32_e32 v29, v11, v11
	v_fmac_f32_e32 v31, v2, v2
	v_fmac_f32_e32 v30, v7, v7
	v_add_f32_e32 v28, v28, v29
	v_fmac_f32_e32 v31, v3, v3
	v_add_f32_e32 v28, v28, v30
	v_add_f32_e32 v28, v28, v31
	s_nop 1
	v_add_f32_dpp v28, v28, v28 quad_perm:[1,0,3,2] row_mask:0xf bank_mask:0xf bound_ctrl:1
	s_nop 1
	v_add_f32_dpp v28, v28, v28 quad_perm:[2,3,0,1] row_mask:0xf bank_mask:0xf bound_ctrl:1
	s_nop 1
	v_add_f32_dpp v28, v28, v28 row_half_mirror row_mask:0xf bank_mask:0xf bound_ctrl:1
	s_nop 1
	v_add_f32_dpp v28, v28, v28 row_mirror row_mask:0xf bank_mask:0xf bound_ctrl:1
	s_nop 1
	v_mov_b32_dpp v25, v28 row_bcast:15 row_mask:0xa bank_mask:0xf
	v_add_f32_e32 v25, v28, v25
	v_mov_b32_e32 v28, v65
	s_nop 1
	v_mov_b32_dpp v28, v25 row_bcast:31 row_mask:0xc bank_mask:0xf
	v_add_f32_e32 v25, v25, v28
	s_nop 0
	v_readlane_b32 s2, v25, 63
	s_and_saveexec_b64 s[36:37], s[0:1]
	s_cbranch_execz .LBB0_810
	v_readlane_b32 s22, v215, 54
	v_readlane_b32 s23, v215, 55
	v_mov_b32_e32 v25, s2
	s_nop 0
	v_lshl_add_u64 v[28:29], v[26:27], 2, s[22:23]
	global_store_dword v[28:29], v25, off
